# baseline (speedup 1.0000x reference)
; __device__ __forceinline__ unsigned cvt_pk_bf16(float lo, float hi) { const f32x2 v = {lo, hi}; const bf16v2 r = __builtin_convertvector(v, bf16v2); return __builtin_bit_cast(unsigned, r); }
;     __device__ __forceinline__ void operator()(const f32x4 (&acc)[2][2][4][2], const Unit& u, int wr, int wc, int fr, int fq) const {
;     ...
;         for (int aim = 0; aim < 4; ++aim) { const int ai = aim >> 1;
;             f32x4 res[4][2][2];
; #pragma unroll
;             for (int m = (aim & 1) * 2; m < (aim & 1) * 2 + 2; ++m)
; #pragma unroll
;                 for (int bj = 0; bj < 2; ++bj)
; #pragma unroll
;                     for (int n = 0; n < 2; ++n) res[m][bj][n] = *(const f32x4*)(C + (size_t)(row0 + ai * HALF + m * 16) * ldc + col0 + bj * HALF + n * 16);
; #pragma unroll
;             for (int m = (aim & 1) * 2; m < (aim & 1) * 2 + 2; ++m) { const int row = row0 + ai * HALF + m * 16; float* rowp = C + (size_t)row * ldc + col0; float sq = 0.f;
; #pragma unroll
;                 for (int bj = 0; bj < 2; ++bj)
; #pragma unroll
;                     for (int n = 0; n < 2; ++n) { f32x4* p = (f32x4*)(rowp + bj * HALF + n * 16); const f32x4 x = res[m][bj][n] + acc[ai][bj][m][n] * scale; *p = x;
;                         if (gain) { sq += x[0] * x[0] + x[1] * x[1] + x[2] * x[2] + x[3] * x[3]; const f32x4 y = x * gv[bj][n];
;                             u32x2 w; w.x = cvt_pk_bf16(y[0], y[1]); w.y = cvt_pk_bf16(y[2], y[3]); *(u32x2*)(XG + (size_t)row * ldc + col0 + bj * HALF + n * 16) = w; } }
;                 if (gain) { sq += __shfl_xor(sq, 16); sq += __shfl_xor(sq, 32); if (fq == 0) part[wc * 256 + ai * HALF + wr * 64 + m * 16 + fr] = sq; } }
.Lepi1_fast:
	v_lshl_or_b32 v206, s63, 8, v233
	v_add_u32_e32 v0, s48, v235
	v_lshlrev_b32_e32 v178, 13, v0
	v_lshl_add_u32 v178, v206, 2, v178
	v_lshlrev_b32_e32 v0, 2, v206
	v_lshrrev_b32_e32 v179, 1, v178
	global_load_dwordx4 v[130:133], v0, s[20:21] offset:0
	global_load_dwordx4 v[134:137], v0, s[20:21] offset:64
	global_load_dwordx4 v[138:141], v0, s[20:21] offset:512
	global_load_dwordx4 v[142:145], v0, s[20:21] offset:576
	s_add_u32 s0, s4, 0x0
	s_addc_u32 s1, s5, 0
	global_load_dwordx4 v[146:149], v178, s[0:1] offset:0
	global_load_dwordx4 v[150:153], v178, s[0:1] offset:64
	global_load_dwordx4 v[154:157], v178, s[0:1] offset:512
	global_load_dwordx4 v[158:161], v178, s[0:1] offset:576
	s_add_u32 s0, s4, 0x20000
	s_addc_u32 s1, s5, 0
	global_load_dwordx4 v[162:165], v178, s[0:1] offset:0
	global_load_dwordx4 v[166:169], v178, s[0:1] offset:64
	global_load_dwordx4 v[170:173], v178, s[0:1] offset:512
	global_load_dwordx4 v[174:177], v178, s[0:1] offset:576
	s_add_u32 s0, s4, 0x40000
	s_addc_u32 s1, s5, 0
	global_load_dwordx4 v[206:209], v178, s[0:1] offset:0
	global_load_dwordx4 v[210:213], v178, s[0:1] offset:64
	global_load_dwordx4 v[214:217], v178, s[0:1] offset:512
	global_load_dwordx4 v[218:221], v178, s[0:1] offset:576
	v_xor_b32_e32 v180, 16, v229
	v_xor_b32_e32 v181, 32, v229
	v_lshlrev_b32_e32 v180, 2, v180
	v_lshlrev_b32_e32 v181, 2, v181
	s_waitcnt vmcnt(8)
	v_pk_fma_f32 v[126:127], s[22:23], v[126:127], v[146:147]
	v_pk_fma_f32 v[128:129], s[22:23], v[128:129], v[148:149]
	v_pk_fma_f32 v[122:123], s[22:23], v[122:123], v[150:151]
	v_pk_fma_f32 v[124:125], s[22:23], v[124:125], v[152:153]
	v_pk_fma_f32 v[94:95], s[22:23], v[94:95], v[154:155]
	v_pk_fma_f32 v[96:97], s[22:23], v[96:97], v[156:157]
	v_pk_fma_f32 v[90:91], s[22:23], v[90:91], v[158:159]
	v_pk_fma_f32 v[92:93], s[22:23], v[92:93], v[160:161]
	s_add_u32 s0, s4, 0x60000
	s_addc_u32 s1, s5, 0
	global_load_dwordx4 v[146:149], v178, s[0:1] offset:0
	global_load_dwordx4 v[150:153], v178, s[0:1] offset:64
	global_load_dwordx4 v[154:157], v178, s[0:1] offset:512
	global_load_dwordx4 v[158:161], v178, s[0:1] offset:576
	s_add_u32 s0, s4, 0x0
	s_addc_u32 s1, s5, 0
	s_add_u32 s12, s14, 0x0
	s_addc_u32 s13, s15, 0
	global_store_dwordx4 v178, v[126:129], s[0:1] offset:0
	global_store_dwordx4 v178, v[122:125], s[0:1] offset:64
	global_store_dwordx4 v178, v[94:97], s[0:1] offset:512
	global_store_dwordx4 v178, v[90:93], s[0:1] offset:576
	v_pk_mul_f32 v[222:223], v[130:131], v[126:127]
	v_pk_mul_f32 v[224:225], v[132:133], v[128:129]
	v_cvt_pk_bf16_f32 v182, v222, v223
	v_cvt_pk_bf16_f32 v183, v224, v225
	global_store_dwordx2 v179, v[182:183], s[12:13] offset:0
	v_pk_mul_f32 v[222:223], v[134:135], v[122:123]
	v_pk_mul_f32 v[224:225], v[136:137], v[124:125]
	v_cvt_pk_bf16_f32 v184, v222, v223
	v_cvt_pk_bf16_f32 v185, v224, v225
	global_store_dwordx2 v179, v[184:185], s[12:13] offset:32
	v_pk_mul_f32 v[222:223], v[138:139], v[94:95]
	v_pk_mul_f32 v[224:225], v[140:141], v[96:97]
	v_cvt_pk_bf16_f32 v182, v222, v223
	v_cvt_pk_bf16_f32 v183, v224, v225
	global_store_dwordx2 v179, v[182:183], s[12:13] offset:256
	v_pk_mul_f32 v[222:223], v[142:143], v[90:91]
	v_pk_mul_f32 v[224:225], v[144:145], v[92:93]
	v_cvt_pk_bf16_f32 v184, v222, v223
	v_cvt_pk_bf16_f32 v185, v224, v225
	global_store_dwordx2 v179, v[184:185], s[12:13] offset:288
	v_mul_f32_e32 v186, v126, v126
	v_fmac_f32_e32 v186, v127, v127
	v_fmac_f32_e32 v186, v128, v128
	v_fmac_f32_e32 v186, v129, v129
	v_fmac_f32_e32 v186, v122, v122
	v_fmac_f32_e32 v186, v123, v123
	v_fmac_f32_e32 v186, v124, v124
	v_fmac_f32_e32 v186, v125, v125
	v_fmac_f32_e32 v186, v94, v94
	v_fmac_f32_e32 v186, v95, v95
	v_fmac_f32_e32 v186, v96, v96
	v_fmac_f32_e32 v186, v97, v97
	v_fmac_f32_e32 v186, v90, v90
	v_fmac_f32_e32 v186, v91, v91
	v_fmac_f32_e32 v186, v92, v92
	v_fmac_f32_e32 v186, v93, v93
	s_nop 0
	v_mov_b32_e32 v126, v186
	s_waitcnt vmcnt(16)
	v_pk_fma_f32 v[118:119], s[22:23], v[118:119], v[162:163]
	v_pk_fma_f32 v[120:121], s[22:23], v[120:121], v[164:165]
	v_pk_fma_f32 v[114:115], s[22:23], v[114:115], v[166:167]
	v_pk_fma_f32 v[116:117], s[22:23], v[116:117], v[168:169]
	v_pk_fma_f32 v[86:87], s[22:23], v[86:87], v[170:171]
	v_pk_fma_f32 v[88:89], s[22:23], v[88:89], v[172:173]
	v_pk_fma_f32 v[82:83], s[22:23], v[82:83], v[174:175]
	v_pk_fma_f32 v[84:85], s[22:23], v[84:85], v[176:177]
	s_add_u32 s0, s4, 0x100000
	s_addc_u32 s1, s5, 0
	global_load_dwordx4 v[162:165], v178, s[0:1] offset:0
	global_load_dwordx4 v[166:169], v178, s[0:1] offset:64
	global_load_dwordx4 v[170:173], v178, s[0:1] offset:512
	global_load_dwordx4 v[174:177], v178, s[0:1] offset:576
	s_add_u32 s0, s4, 0x20000
	s_addc_u32 s1, s5, 0
	s_add_u32 s12, s14, 0x10000
	s_addc_u32 s13, s15, 0
	global_store_dwordx4 v178, v[118:121], s[0:1] offset:0
	global_store_dwordx4 v178, v[114:117], s[0:1] offset:64
	global_store_dwordx4 v178, v[86:89], s[0:1] offset:512
	global_store_dwordx4 v178, v[82:85], s[0:1] offset:576
	v_pk_mul_f32 v[222:223], v[130:131], v[118:119]
	v_pk_mul_f32 v[224:225], v[132:133], v[120:121]
	v_cvt_pk_bf16_f32 v182, v222, v223
	v_cvt_pk_bf16_f32 v183, v224, v225
	global_store_dwordx2 v179, v[182:183], s[12:13] offset:0
	v_pk_mul_f32 v[222:223], v[134:135], v[114:115]
	v_pk_mul_f32 v[224:225], v[136:137], v[116:117]
	v_cvt_pk_bf16_f32 v184, v222, v223
	v_cvt_pk_bf16_f32 v185, v224, v225
	global_store_dwordx2 v179, v[184:185], s[12:13] offset:32
	v_pk_mul_f32 v[222:223], v[138:139], v[86:87]
	v_pk_mul_f32 v[224:225], v[140:141], v[88:89]
	v_cvt_pk_bf16_f32 v182, v222, v223
	v_cvt_pk_bf16_f32 v183, v224, v225
	global_store_dwordx2 v179, v[182:183], s[12:13] offset:256
	v_pk_mul_f32 v[222:223], v[142:143], v[82:83]
	v_pk_mul_f32 v[224:225], v[144:145], v[84:85]
	v_cvt_pk_bf16_f32 v184, v222, v223
	v_cvt_pk_bf16_f32 v185, v224, v225
	global_store_dwordx2 v179, v[184:185], s[12:13] offset:288
	v_mul_f32_e32 v186, v118, v118
	v_fmac_f32_e32 v186, v119, v119
	v_fmac_f32_e32 v186, v120, v120
	v_fmac_f32_e32 v186, v121, v121
	v_fmac_f32_e32 v186, v114, v114
	v_fmac_f32_e32 v186, v115, v115
	v_fmac_f32_e32 v186, v116, v116
	v_fmac_f32_e32 v186, v117, v117
	v_fmac_f32_e32 v186, v86, v86
	v_fmac_f32_e32 v186, v87, v87
	v_fmac_f32_e32 v186, v88, v88
	v_fmac_f32_e32 v186, v89, v89
	v_fmac_f32_e32 v186, v82, v82
	v_fmac_f32_e32 v186, v83, v83
	v_fmac_f32_e32 v186, v84, v84
	v_fmac_f32_e32 v186, v85, v85
	s_nop 0
	v_mov_b32_e32 v118, v186
	s_waitcnt vmcnt(24)
; __device__ __forceinline__ unsigned cvt_pk_bf16(float lo, float hi) { const f32x2 v = {lo, hi}; const bf16v2 r = __builtin_convertvector(v, bf16v2); return __builtin_bit_cast(unsigned, r); }
;     __device__ __forceinline__ void operator()(const f32x4 (&acc)[2][2][4][2], const Unit& u, int wr, int wc, int fr, int fq) const {
;     ...
;         for (int aim = 0; aim < 4; ++aim) { const int ai = aim >> 1;
;             f32x4 res[4][2][2];
; #pragma unroll
;             for (int m = (aim & 1) * 2; m < (aim & 1) * 2 + 2; ++m)
; #pragma unroll
;                 for (int bj = 0; bj < 2; ++bj)
; #pragma unroll
;                     for (int n = 0; n < 2; ++n) res[m][bj][n] = *(const f32x4*)(C + (size_t)(row0 + ai * HALF + m * 16) * ldc + col0 + bj * HALF + n * 16);
; #pragma unroll
;             for (int m = (aim & 1) * 2; m < (aim & 1) * 2 + 2; ++m) { const int row = row0 + ai * HALF + m * 16; float* rowp = C + (size_t)row * ldc + col0; float sq = 0.f;
; #pragma unroll
;                 for (int bj = 0; bj < 2; ++bj)
; #pragma unroll
;                     for (int n = 0; n < 2; ++n) { f32x4* p = (f32x4*)(rowp + bj * HALF + n * 16); const f32x4 x = res[m][bj][n] + acc[ai][bj][m][n] * scale; *p = x;
;                         if (gain) { sq += x[0] * x[0] + x[1] * x[1] + x[2] * x[2] + x[3] * x[3]; const f32x4 y = x * gv[bj][n];
;                             u32x2 w; w.x = cvt_pk_bf16(y[0], y[1]); w.y = cvt_pk_bf16(y[2], y[3]); *(u32x2*)(XG + (size_t)row * ldc + col0 + bj * HALF + n * 16) = w; } }
;                 if (gain) { sq += __shfl_xor(sq, 16); sq += __shfl_xor(sq, 32); if (fq == 0) part[wc * 256 + ai * HALF + wr * 64 + m * 16 + fr] = sq; } }
	v_pk_fma_f32 v[110:111], s[22:23], v[110:111], v[206:207]
	v_pk_fma_f32 v[112:113], s[22:23], v[112:113], v[208:209]
	v_pk_fma_f32 v[106:107], s[22:23], v[106:107], v[210:211]
	v_pk_fma_f32 v[108:109], s[22:23], v[108:109], v[212:213]
	v_pk_fma_f32 v[78:79], s[22:23], v[78:79], v[214:215]
	v_pk_fma_f32 v[80:81], s[22:23], v[80:81], v[216:217]
	v_pk_fma_f32 v[74:75], s[22:23], v[74:75], v[218:219]
	v_pk_fma_f32 v[76:77], s[22:23], v[76:77], v[220:221]
	s_add_u32 s0, s4, 0x120000
	s_addc_u32 s1, s5, 0
	global_load_dwordx4 v[206:209], v178, s[0:1] offset:0
	global_load_dwordx4 v[210:213], v178, s[0:1] offset:64
	global_load_dwordx4 v[214:217], v178, s[0:1] offset:512
	global_load_dwordx4 v[218:221], v178, s[0:1] offset:576
	s_add_u32 s0, s4, 0x40000
	s_addc_u32 s1, s5, 0
	s_add_u32 s12, s14, 0x20000
	s_addc_u32 s13, s15, 0
	global_store_dwordx4 v178, v[110:113], s[0:1] offset:0
	global_store_dwordx4 v178, v[106:109], s[0:1] offset:64
	global_store_dwordx4 v178, v[78:81], s[0:1] offset:512
	global_store_dwordx4 v178, v[74:77], s[0:1] offset:576
	v_pk_mul_f32 v[222:223], v[130:131], v[110:111]
	v_pk_mul_f32 v[224:225], v[132:133], v[112:113]
	v_cvt_pk_bf16_f32 v182, v222, v223
	v_cvt_pk_bf16_f32 v183, v224, v225
	global_store_dwordx2 v179, v[182:183], s[12:13] offset:0
	v_pk_mul_f32 v[222:223], v[134:135], v[106:107]
	v_pk_mul_f32 v[224:225], v[136:137], v[108:109]
	v_cvt_pk_bf16_f32 v184, v222, v223
	v_cvt_pk_bf16_f32 v185, v224, v225
	global_store_dwordx2 v179, v[184:185], s[12:13] offset:32
	v_pk_mul_f32 v[222:223], v[138:139], v[78:79]
	v_pk_mul_f32 v[224:225], v[140:141], v[80:81]
	v_cvt_pk_bf16_f32 v182, v222, v223
	v_cvt_pk_bf16_f32 v183, v224, v225
	global_store_dwordx2 v179, v[182:183], s[12:13] offset:256
	v_pk_mul_f32 v[222:223], v[142:143], v[74:75]
	v_pk_mul_f32 v[224:225], v[144:145], v[76:77]
	v_cvt_pk_bf16_f32 v184, v222, v223
	v_cvt_pk_bf16_f32 v185, v224, v225
	global_store_dwordx2 v179, v[184:185], s[12:13] offset:288
	v_mul_f32_e32 v186, v110, v110
	v_fmac_f32_e32 v186, v111, v111
	v_fmac_f32_e32 v186, v112, v112
	v_fmac_f32_e32 v186, v113, v113
	v_fmac_f32_e32 v186, v106, v106
	v_fmac_f32_e32 v186, v107, v107
	v_fmac_f32_e32 v186, v108, v108
	v_fmac_f32_e32 v186, v109, v109
	v_fmac_f32_e32 v186, v78, v78
	v_fmac_f32_e32 v186, v79, v79
	v_fmac_f32_e32 v186, v80, v80
	v_fmac_f32_e32 v186, v81, v81
	v_fmac_f32_e32 v186, v74, v74
	v_fmac_f32_e32 v186, v75, v75
	v_fmac_f32_e32 v186, v76, v76
	v_fmac_f32_e32 v186, v77, v77
	s_nop 0
	v_mov_b32_e32 v110, v186
	s_waitcnt vmcnt(32)
	v_pk_fma_f32 v[102:103], s[22:23], v[102:103], v[146:147]
	v_pk_fma_f32 v[104:105], s[22:23], v[104:105], v[148:149]
	v_pk_fma_f32 v[98:99], s[22:23], v[98:99], v[150:151]
	v_pk_fma_f32 v[100:101], s[22:23], v[100:101], v[152:153]
	v_pk_fma_f32 v[70:71], s[22:23], v[70:71], v[154:155]
	v_pk_fma_f32 v[72:73], s[22:23], v[72:73], v[156:157]
	v_pk_fma_f32 v[66:67], s[22:23], v[66:67], v[158:159]
	v_pk_fma_f32 v[68:69], s[22:23], v[68:69], v[160:161]
	s_add_u32 s0, s4, 0x140000
	s_addc_u32 s1, s5, 0
	global_load_dwordx4 v[146:149], v178, s[0:1] offset:0
	global_load_dwordx4 v[150:153], v178, s[0:1] offset:64
	global_load_dwordx4 v[154:157], v178, s[0:1] offset:512
	global_load_dwordx4 v[158:161], v178, s[0:1] offset:576
	s_add_u32 s0, s4, 0x60000
	s_addc_u32 s1, s5, 0
	s_add_u32 s12, s14, 0x30000
	s_addc_u32 s13, s15, 0
	global_store_dwordx4 v178, v[102:105], s[0:1] offset:0
	global_store_dwordx4 v178, v[98:101], s[0:1] offset:64
	global_store_dwordx4 v178, v[70:73], s[0:1] offset:512
	global_store_dwordx4 v178, v[66:69], s[0:1] offset:576
	v_pk_mul_f32 v[222:223], v[130:131], v[102:103]
	v_pk_mul_f32 v[224:225], v[132:133], v[104:105]
	v_cvt_pk_bf16_f32 v182, v222, v223
	v_cvt_pk_bf16_f32 v183, v224, v225
	global_store_dwordx2 v179, v[182:183], s[12:13] offset:0
	v_pk_mul_f32 v[222:223], v[134:135], v[98:99]
	v_pk_mul_f32 v[224:225], v[136:137], v[100:101]
	v_cvt_pk_bf16_f32 v184, v222, v223
	v_cvt_pk_bf16_f32 v185, v224, v225
	global_store_dwordx2 v179, v[184:185], s[12:13] offset:32
	v_pk_mul_f32 v[222:223], v[138:139], v[70:71]
	v_pk_mul_f32 v[224:225], v[140:141], v[72:73]
	v_cvt_pk_bf16_f32 v182, v222, v223
	v_cvt_pk_bf16_f32 v183, v224, v225
	global_store_dwordx2 v179, v[182:183], s[12:13] offset:256
	v_pk_mul_f32 v[222:223], v[142:143], v[66:67]
	v_pk_mul_f32 v[224:225], v[144:145], v[68:69]
	v_cvt_pk_bf16_f32 v184, v222, v223
	v_cvt_pk_bf16_f32 v185, v224, v225
	global_store_dwordx2 v179, v[184:185], s[12:13] offset:288
	v_mul_f32_e32 v186, v102, v102
	v_fmac_f32_e32 v186, v103, v103
	v_fmac_f32_e32 v186, v104, v104
	v_fmac_f32_e32 v186, v105, v105
	v_fmac_f32_e32 v186, v98, v98
	v_fmac_f32_e32 v186, v99, v99
	v_fmac_f32_e32 v186, v100, v100
	v_fmac_f32_e32 v186, v101, v101
	v_fmac_f32_e32 v186, v70, v70
	v_fmac_f32_e32 v186, v71, v71
	v_fmac_f32_e32 v186, v72, v72
	v_fmac_f32_e32 v186, v73, v73
	v_fmac_f32_e32 v186, v66, v66
	v_fmac_f32_e32 v186, v67, v67
	v_fmac_f32_e32 v186, v68, v68
	v_fmac_f32_e32 v186, v69, v69
	s_nop 0
	v_mov_b32_e32 v102, v186
	s_waitcnt vmcnt(32)
; __device__ __forceinline__ unsigned cvt_pk_bf16(float lo, float hi) { const f32x2 v = {lo, hi}; const bf16v2 r = __builtin_convertvector(v, bf16v2); return __builtin_bit_cast(unsigned, r); }
;     __device__ __forceinline__ void operator()(const f32x4 (&acc)[2][2][4][2], const Unit& u, int wr, int wc, int fr, int fq) const {
;     ...
;         for (int aim = 0; aim < 4; ++aim) { const int ai = aim >> 1;
;             f32x4 res[4][2][2];
; #pragma unroll
;             for (int m = (aim & 1) * 2; m < (aim & 1) * 2 + 2; ++m)
; #pragma unroll
;                 for (int bj = 0; bj < 2; ++bj)
; #pragma unroll
;                     for (int n = 0; n < 2; ++n) res[m][bj][n] = *(const f32x4*)(C + (size_t)(row0 + ai * HALF + m * 16) * ldc + col0 + bj * HALF + n * 16);
; #pragma unroll
;             for (int m = (aim & 1) * 2; m < (aim & 1) * 2 + 2; ++m) { const int row = row0 + ai * HALF + m * 16; float* rowp = C + (size_t)row * ldc + col0; float sq = 0.f;
; #pragma unroll
;                 for (int bj = 0; bj < 2; ++bj)
; #pragma unroll
;                     for (int n = 0; n < 2; ++n) { f32x4* p = (f32x4*)(rowp + bj * HALF + n * 16); const f32x4 x = res[m][bj][n] + acc[ai][bj][m][n] * scale; *p = x;
;                         if (gain) { sq += x[0] * x[0] + x[1] * x[1] + x[2] * x[2] + x[3] * x[3]; const f32x4 y = x * gv[bj][n];
;                             u32x2 w; w.x = cvt_pk_bf16(y[0], y[1]); w.y = cvt_pk_bf16(y[2], y[3]); *(u32x2*)(XG + (size_t)row * ldc + col0 + bj * HALF + n * 16) = w; } }
;                 if (gain) { sq += __shfl_xor(sq, 16); sq += __shfl_xor(sq, 32); if (fq == 0) part[wc * 256 + ai * HALF + wr * 64 + m * 16 + fr] = sq; } }
	v_pk_fma_f32 v[62:63], s[22:23], v[62:63], v[162:163]
	v_pk_fma_f32 v[64:65], s[22:23], v[64:65], v[164:165]
	v_pk_fma_f32 v[58:59], s[22:23], v[58:59], v[166:167]
	v_pk_fma_f32 v[60:61], s[22:23], v[60:61], v[168:169]
	v_pk_fma_f32 v[30:31], s[22:23], v[30:31], v[170:171]
	v_pk_fma_f32 v[32:33], s[22:23], v[32:33], v[172:173]
	v_pk_fma_f32 v[26:27], s[22:23], v[26:27], v[174:175]
	v_pk_fma_f32 v[28:29], s[22:23], v[28:29], v[176:177]
	s_add_u32 s0, s4, 0x160000
	s_addc_u32 s1, s5, 0
	global_load_dwordx4 v[162:165], v178, s[0:1] offset:0
	global_load_dwordx4 v[166:169], v178, s[0:1] offset:64
	global_load_dwordx4 v[170:173], v178, s[0:1] offset:512
	global_load_dwordx4 v[174:177], v178, s[0:1] offset:576
	s_add_u32 s0, s4, 0x100000
	s_addc_u32 s1, s5, 0
	s_add_u32 s12, s14, 0x80000
	s_addc_u32 s13, s15, 0
	global_store_dwordx4 v178, v[62:65], s[0:1] offset:0
	global_store_dwordx4 v178, v[58:61], s[0:1] offset:64
	global_store_dwordx4 v178, v[30:33], s[0:1] offset:512
	global_store_dwordx4 v178, v[26:29], s[0:1] offset:576
	v_pk_mul_f32 v[222:223], v[130:131], v[62:63]
	v_pk_mul_f32 v[224:225], v[132:133], v[64:65]
	v_cvt_pk_bf16_f32 v182, v222, v223
	v_cvt_pk_bf16_f32 v183, v224, v225
	global_store_dwordx2 v179, v[182:183], s[12:13] offset:0
	v_pk_mul_f32 v[222:223], v[134:135], v[58:59]
	v_pk_mul_f32 v[224:225], v[136:137], v[60:61]
	v_cvt_pk_bf16_f32 v184, v222, v223
	v_cvt_pk_bf16_f32 v185, v224, v225
	global_store_dwordx2 v179, v[184:185], s[12:13] offset:32
	v_pk_mul_f32 v[222:223], v[138:139], v[30:31]
	v_pk_mul_f32 v[224:225], v[140:141], v[32:33]
	v_cvt_pk_bf16_f32 v182, v222, v223
	v_cvt_pk_bf16_f32 v183, v224, v225
	global_store_dwordx2 v179, v[182:183], s[12:13] offset:256
	v_pk_mul_f32 v[222:223], v[142:143], v[26:27]
	v_pk_mul_f32 v[224:225], v[144:145], v[28:29]
	v_cvt_pk_bf16_f32 v184, v222, v223
	v_cvt_pk_bf16_f32 v185, v224, v225
	global_store_dwordx2 v179, v[184:185], s[12:13] offset:288
	v_mul_f32_e32 v186, v62, v62
	v_fmac_f32_e32 v186, v63, v63
	v_fmac_f32_e32 v186, v64, v64
	v_fmac_f32_e32 v186, v65, v65
	v_fmac_f32_e32 v186, v58, v58
	v_fmac_f32_e32 v186, v59, v59
	v_fmac_f32_e32 v186, v60, v60
	v_fmac_f32_e32 v186, v61, v61
	v_fmac_f32_e32 v186, v30, v30
	v_fmac_f32_e32 v186, v31, v31
	v_fmac_f32_e32 v186, v32, v32
	v_fmac_f32_e32 v186, v33, v33
	v_fmac_f32_e32 v186, v26, v26
	v_fmac_f32_e32 v186, v27, v27
	v_fmac_f32_e32 v186, v28, v28
	v_fmac_f32_e32 v186, v29, v29
	s_nop 0
	v_mov_b32_e32 v62, v186
	s_waitcnt vmcnt(32)
	v_pk_fma_f32 v[54:55], s[22:23], v[54:55], v[206:207]
	v_pk_fma_f32 v[56:57], s[22:23], v[56:57], v[208:209]
	v_pk_fma_f32 v[50:51], s[22:23], v[50:51], v[210:211]
	v_pk_fma_f32 v[52:53], s[22:23], v[52:53], v[212:213]
	v_pk_fma_f32 v[22:23], s[22:23], v[22:23], v[214:215]
	v_pk_fma_f32 v[24:25], s[22:23], v[24:25], v[216:217]
	v_pk_fma_f32 v[18:19], s[22:23], v[18:19], v[218:219]
	v_pk_fma_f32 v[20:21], s[22:23], v[20:21], v[220:221]
	s_add_u32 s0, s4, 0x120000
	s_addc_u32 s1, s5, 0
	s_add_u32 s12, s14, 0x90000
	s_addc_u32 s13, s15, 0
	global_store_dwordx4 v178, v[54:57], s[0:1] offset:0
	global_store_dwordx4 v178, v[50:53], s[0:1] offset:64
	global_store_dwordx4 v178, v[22:25], s[0:1] offset:512
	global_store_dwordx4 v178, v[18:21], s[0:1] offset:576
	v_pk_mul_f32 v[222:223], v[130:131], v[54:55]
	v_pk_mul_f32 v[224:225], v[132:133], v[56:57]
	v_cvt_pk_bf16_f32 v182, v222, v223
	v_cvt_pk_bf16_f32 v183, v224, v225
	global_store_dwordx2 v179, v[182:183], s[12:13] offset:0
	v_pk_mul_f32 v[222:223], v[134:135], v[50:51]
	v_pk_mul_f32 v[224:225], v[136:137], v[52:53]
	v_cvt_pk_bf16_f32 v184, v222, v223
	v_cvt_pk_bf16_f32 v185, v224, v225
	global_store_dwordx2 v179, v[184:185], s[12:13] offset:32
	v_pk_mul_f32 v[222:223], v[138:139], v[22:23]
	v_pk_mul_f32 v[224:225], v[140:141], v[24:25]
	v_cvt_pk_bf16_f32 v182, v222, v223
	v_cvt_pk_bf16_f32 v183, v224, v225
	global_store_dwordx2 v179, v[182:183], s[12:13] offset:256
	v_pk_mul_f32 v[222:223], v[142:143], v[18:19]
	v_pk_mul_f32 v[224:225], v[144:145], v[20:21]
	v_cvt_pk_bf16_f32 v184, v222, v223
	v_cvt_pk_bf16_f32 v185, v224, v225
	global_store_dwordx2 v179, v[184:185], s[12:13] offset:288
	v_mul_f32_e32 v186, v54, v54
	v_fmac_f32_e32 v186, v55, v55
	v_fmac_f32_e32 v186, v56, v56
	v_fmac_f32_e32 v186, v57, v57
	v_fmac_f32_e32 v186, v50, v50
	v_fmac_f32_e32 v186, v51, v51
	v_fmac_f32_e32 v186, v52, v52
	v_fmac_f32_e32 v186, v53, v53
	v_fmac_f32_e32 v186, v22, v22
	v_fmac_f32_e32 v186, v23, v23
	v_fmac_f32_e32 v186, v24, v24
	v_fmac_f32_e32 v186, v25, v25
	v_fmac_f32_e32 v186, v18, v18
	v_fmac_f32_e32 v186, v19, v19
	v_fmac_f32_e32 v186, v20, v20
	v_fmac_f32_e32 v186, v21, v21
	s_nop 0
	v_mov_b32_e32 v54, v186
	s_waitcnt vmcnt(28)
; __device__ __forceinline__ unsigned cvt_pk_bf16(float lo, float hi) { const f32x2 v = {lo, hi}; const bf16v2 r = __builtin_convertvector(v, bf16v2); return __builtin_bit_cast(unsigned, r); }
;     __device__ __forceinline__ void operator()(const f32x4 (&acc)[2][2][4][2], const Unit& u, int wr, int wc, int fr, int fq) const {
;     ...
;         for (int aim = 0; aim < 4; ++aim) { const int ai = aim >> 1;
;             f32x4 res[4][2][2];
; #pragma unroll
;             for (int m = (aim & 1) * 2; m < (aim & 1) * 2 + 2; ++m)
; #pragma unroll
;                 for (int bj = 0; bj < 2; ++bj)
; #pragma unroll
;                     for (int n = 0; n < 2; ++n) res[m][bj][n] = *(const f32x4*)(C + (size_t)(row0 + ai * HALF + m * 16) * ldc + col0 + bj * HALF + n * 16);
; #pragma unroll
;             for (int m = (aim & 1) * 2; m < (aim & 1) * 2 + 2; ++m) { const int row = row0 + ai * HALF + m * 16; float* rowp = C + (size_t)row * ldc + col0; float sq = 0.f;
; #pragma unroll
;                 for (int bj = 0; bj < 2; ++bj)
; #pragma unroll
;                     for (int n = 0; n < 2; ++n) { f32x4* p = (f32x4*)(rowp + bj * HALF + n * 16); const f32x4 x = res[m][bj][n] + acc[ai][bj][m][n] * scale; *p = x;
;                         if (gain) { sq += x[0] * x[0] + x[1] * x[1] + x[2] * x[2] + x[3] * x[3]; const f32x4 y = x * gv[bj][n];
;                             u32x2 w; w.x = cvt_pk_bf16(y[0], y[1]); w.y = cvt_pk_bf16(y[2], y[3]); *(u32x2*)(XG + (size_t)row * ldc + col0 + bj * HALF + n * 16) = w; } }
;                 if (gain) { sq += __shfl_xor(sq, 16); sq += __shfl_xor(sq, 32); if (fq == 0) part[wc * 256 + ai * HALF + wr * 64 + m * 16 + fr] = sq; } }
	v_pk_fma_f32 v[46:47], s[22:23], v[46:47], v[146:147]
	v_pk_fma_f32 v[48:49], s[22:23], v[48:49], v[148:149]
	v_pk_fma_f32 v[42:43], s[22:23], v[42:43], v[150:151]
	v_pk_fma_f32 v[44:45], s[22:23], v[44:45], v[152:153]
	v_pk_fma_f32 v[14:15], s[22:23], v[14:15], v[154:155]
	v_pk_fma_f32 v[16:17], s[22:23], v[16:17], v[156:157]
	v_pk_fma_f32 v[10:11], s[22:23], v[10:11], v[158:159]
	v_pk_fma_f32 v[12:13], s[22:23], v[12:13], v[160:161]
	s_add_u32 s0, s4, 0x140000
	s_addc_u32 s1, s5, 0
	s_add_u32 s12, s14, 0xa0000
	s_addc_u32 s13, s15, 0
	global_store_dwordx4 v178, v[46:49], s[0:1] offset:0
	global_store_dwordx4 v178, v[42:45], s[0:1] offset:64
	global_store_dwordx4 v178, v[14:17], s[0:1] offset:512
	global_store_dwordx4 v178, v[10:13], s[0:1] offset:576
	v_pk_mul_f32 v[222:223], v[130:131], v[46:47]
	v_pk_mul_f32 v[224:225], v[132:133], v[48:49]
	v_cvt_pk_bf16_f32 v182, v222, v223
	v_cvt_pk_bf16_f32 v183, v224, v225
	global_store_dwordx2 v179, v[182:183], s[12:13] offset:0
	v_pk_mul_f32 v[222:223], v[134:135], v[42:43]
	v_pk_mul_f32 v[224:225], v[136:137], v[44:45]
	v_cvt_pk_bf16_f32 v184, v222, v223
	v_cvt_pk_bf16_f32 v185, v224, v225
	global_store_dwordx2 v179, v[184:185], s[12:13] offset:32
	v_pk_mul_f32 v[222:223], v[138:139], v[14:15]
	v_pk_mul_f32 v[224:225], v[140:141], v[16:17]
	v_cvt_pk_bf16_f32 v182, v222, v223
	v_cvt_pk_bf16_f32 v183, v224, v225
	global_store_dwordx2 v179, v[182:183], s[12:13] offset:256
	v_pk_mul_f32 v[222:223], v[142:143], v[10:11]
	v_pk_mul_f32 v[224:225], v[144:145], v[12:13]
	v_cvt_pk_bf16_f32 v184, v222, v223
	v_cvt_pk_bf16_f32 v185, v224, v225
	global_store_dwordx2 v179, v[184:185], s[12:13] offset:288
	v_mul_f32_e32 v186, v46, v46
	v_fmac_f32_e32 v186, v47, v47
	v_fmac_f32_e32 v186, v48, v48
	v_fmac_f32_e32 v186, v49, v49
	v_fmac_f32_e32 v186, v42, v42
	v_fmac_f32_e32 v186, v43, v43
	v_fmac_f32_e32 v186, v44, v44
	v_fmac_f32_e32 v186, v45, v45
	v_fmac_f32_e32 v186, v14, v14
	v_fmac_f32_e32 v186, v15, v15
	v_fmac_f32_e32 v186, v16, v16
	v_fmac_f32_e32 v186, v17, v17
	v_fmac_f32_e32 v186, v10, v10
	v_fmac_f32_e32 v186, v11, v11
	v_fmac_f32_e32 v186, v12, v12
	v_fmac_f32_e32 v186, v13, v13
	s_nop 0
	v_mov_b32_e32 v46, v186
	s_waitcnt vmcnt(24)
	v_pk_fma_f32 v[38:39], s[22:23], v[38:39], v[162:163]
	v_pk_fma_f32 v[40:41], s[22:23], v[40:41], v[164:165]
	v_pk_fma_f32 v[34:35], s[22:23], v[34:35], v[166:167]
	v_pk_fma_f32 v[36:37], s[22:23], v[36:37], v[168:169]
	v_pk_fma_f32 v[6:7], s[22:23], v[6:7], v[170:171]
	v_pk_fma_f32 v[8:9], s[22:23], v[8:9], v[172:173]
	v_pk_fma_f32 v[2:3], s[22:23], v[2:3], v[174:175]
	v_pk_fma_f32 v[4:5], s[22:23], v[4:5], v[176:177]
	s_add_u32 s0, s4, 0x160000
	s_addc_u32 s1, s5, 0
	s_add_u32 s12, s14, 0xb0000
	s_addc_u32 s13, s15, 0
	global_store_dwordx4 v178, v[38:41], s[0:1] offset:0
	global_store_dwordx4 v178, v[34:37], s[0:1] offset:64
	global_store_dwordx4 v178, v[6:9], s[0:1] offset:512
	global_store_dwordx4 v178, v[2:5], s[0:1] offset:576
	v_pk_mul_f32 v[222:223], v[130:131], v[38:39]
	v_pk_mul_f32 v[224:225], v[132:133], v[40:41]
	v_cvt_pk_bf16_f32 v182, v222, v223
	v_cvt_pk_bf16_f32 v183, v224, v225
	global_store_dwordx2 v179, v[182:183], s[12:13] offset:0
	v_pk_mul_f32 v[222:223], v[134:135], v[34:35]
	v_pk_mul_f32 v[224:225], v[136:137], v[36:37]
	v_cvt_pk_bf16_f32 v184, v222, v223
	v_cvt_pk_bf16_f32 v185, v224, v225
	global_store_dwordx2 v179, v[184:185], s[12:13] offset:32
	v_pk_mul_f32 v[222:223], v[138:139], v[6:7]
	v_pk_mul_f32 v[224:225], v[140:141], v[8:9]
	v_cvt_pk_bf16_f32 v182, v222, v223
	v_cvt_pk_bf16_f32 v183, v224, v225
	global_store_dwordx2 v179, v[182:183], s[12:13] offset:256
	v_pk_mul_f32 v[222:223], v[142:143], v[2:3]
	v_pk_mul_f32 v[224:225], v[144:145], v[4:5]
	v_cvt_pk_bf16_f32 v184, v222, v223
	v_cvt_pk_bf16_f32 v185, v224, v225
	global_store_dwordx2 v179, v[184:185], s[12:13] offset:288
	v_mul_f32_e32 v186, v38, v38
	v_fmac_f32_e32 v186, v39, v39
	v_fmac_f32_e32 v186, v40, v40
	v_fmac_f32_e32 v186, v41, v41
	v_fmac_f32_e32 v186, v34, v34
	v_fmac_f32_e32 v186, v35, v35
	v_fmac_f32_e32 v186, v36, v36
	v_fmac_f32_e32 v186, v37, v37
	v_fmac_f32_e32 v186, v6, v6
	v_fmac_f32_e32 v186, v7, v7
	v_fmac_f32_e32 v186, v8, v8
	v_fmac_f32_e32 v186, v9, v9
	v_fmac_f32_e32 v186, v2, v2
	v_fmac_f32_e32 v186, v3, v3
	v_fmac_f32_e32 v186, v4, v4
	v_fmac_f32_e32 v186, v5, v5
	s_nop 0
	v_mov_b32_e32 v38, v186
	ds_bpermute_b32 v127, v180, v126
	ds_bpermute_b32 v119, v180, v118
	ds_bpermute_b32 v111, v180, v110
	ds_bpermute_b32 v103, v180, v102
	ds_bpermute_b32 v63, v180, v62
	ds_bpermute_b32 v55, v180, v54
	ds_bpermute_b32 v47, v180, v46
	ds_bpermute_b32 v39, v180, v38
	s_waitcnt lgkmcnt(0)
	v_add_f32_e32 v126, v126, v127
	v_add_f32_e32 v118, v118, v119
	v_add_f32_e32 v110, v110, v111
	v_add_f32_e32 v102, v102, v103
	v_add_f32_e32 v62, v62, v63
	v_add_f32_e32 v54, v54, v55
	v_add_f32_e32 v46, v46, v47
	v_add_f32_e32 v38, v38, v39
	ds_bpermute_b32 v127, v181, v126
	ds_bpermute_b32 v119, v181, v118
	ds_bpermute_b32 v111, v181, v110
	ds_bpermute_b32 v103, v181, v102
	ds_bpermute_b32 v63, v181, v62
	ds_bpermute_b32 v55, v181, v54
	ds_bpermute_b32 v47, v181, v46
	ds_bpermute_b32 v39, v181, v38
	s_waitcnt lgkmcnt(0)
	v_add_f32_e32 v126, v126, v127
	v_add_f32_e32 v118, v118, v119
	v_add_f32_e32 v110, v110, v111
	v_add_f32_e32 v102, v102, v103
	v_add_f32_e32 v62, v62, v63
	v_add_f32_e32 v54, v54, v55
	v_add_f32_e32 v46, v46, v47
	v_add_f32_e32 v38, v38, v39
	s_and_saveexec_b64 s[44:45], s[38:39]
	ds_write_b32 v231, v126 offset:0
	ds_write_b32 v231, v118 offset:64
	ds_write_b32 v231, v110 offset:128
	ds_write_b32 v231, v102 offset:192
	ds_write_b32 v231, v62 offset:512
	ds_write_b32 v231, v54 offset:576
	ds_write_b32 v231, v46 offset:640
	ds_write_b32 v231, v38 offset:704
	s_or_b64 exec, exec, s[44:45]
	s_branch .Lepi1_join
